# c13: GEMM tile prologues zero the accumulators while the first LDS-DMA stage is in flight
# baseline (speedup 1.0000x reference)
; #define LDSAS __attribute__((address_space(3)))
; #define G_ISSUE(kt, st) do { G_ISSUE1(kt, st, 0); G_ISSUE1(kt, st, 1); G_ISSUE1(kt, st, 2); G_ISSUE1(kt, st, 3); } while (0)
; template <bool LOWREG = false>
; __device__ __forceinline__ void gemm_core(const bf16_t* __restrict__ A, int lda, const bf16_t* __restrict__ Bt, int ldb, int K, f32x4 (&acc)[8][4], unsigned char* smem, int tid) {
;     asm volatile("" : "+v"(tid));
;     const int lane = tid & 63, w = __builtin_amdgcn_readfirstlane(tid >> 6), wm = w >> 2, wn = w & 3, idx = lane & 15, kq = lane >> 4;
;     unsigned offA[4], offB[4];
; #pragma unroll
;     for (int j = 0; j < 4; ++j) { const int row = (j * 8 + w) * 8 + (lane >> 3), c = (lane & 7) ^ ((row >> 1) & 7);
;         offA[j] = (unsigned)(row * lda + c * 8) * 2u; offB[j] = (unsigned)(row * ldb + c * 8) * 2u; }
; #pragma unroll
;     for (int mi = 0; mi < 8; ++mi)
; #pragma unroll
;         for (int ni = 0; ni < 4; ++ni) acc[mi][ni] = (f32x4){0.f, 0.f, 0.f, 0.f};
;     LDSAS unsigned char* lds = (LDSAS unsigned char*)smem;
;     ...
;     const int nk = K >> 6;
;     G_ISSUE(0, 0);
;     asm volatile("s_waitcnt vmcnt(0)" ::: "memory");
;     __syncthreads();
;     const int swz = (idx >> 1) & 7;
;     const int aoff = (wm * 128 + idx) * 128, boff = G_AB + (wn * 64 + idx) * 128;
.LBB0_254:
	s_mul_hi_i32 s9, s60, 0x78787879
	s_lshr_b32 s11, s9, 31
	s_ashr_i32 s9, s9, 7
	s_add_i32 s9, s9, s11
	s_mul_i32 s11, s9, 0x110
	s_sub_i32 s11, s60, s11
	s_and_b32 s12, s11, 7
	s_mul_i32 s12, s12, 34
	s_ashr_i32 s11, s11, 3
	s_add_i32 s12, s12, s11
	s_lshl_b32 s11, s12, 8
	s_lshl_b32 s9, s9, 11
	s_and_b32 s11, s11, 0x700
	s_or_b32 s56, s11, s9
	s_lshl_b32 s11, s12, 5
	s_ashr_i32 s57, s56, 31
	s_and_b32 s36, s11, 0xffffff00
	s_lshl_b64 s[16:17], s[56:57], 11
	s_add_u32 s18, s92, s16
	s_addc_u32 s19, s93, s17
	s_ashr_i32 s37, s36, 31
	s_lshl_b64 s[20:21], s[36:37], 11
	v_mov_b32_e32 v0, v210
	s_add_u32 s22, s94, s20
	s_addc_u32 s23, s95, s21
	v_readfirstlane_b32 s12, v0
	s_ashr_i32 s24, s12, 6
	s_and_b32 s101, s24, 3
	s_cmp_lg_u32 s101, 0
	s_cselect_b32 s101, 1, 0
	s_cmp_eq_u32 s36, 0x2100
	s_cselect_b32 s101, s101, 0
	v_bfe_u32 v2, v0, 3, 3
	v_lshl_or_b32 v3, s24, 3, v2
	v_lshrrev_b32_e32 v4, 1, v3
	v_xor_b32_e32 v4, v4, v0
	v_lshlrev_b32_e32 v4, 4, v4
	s_lshl_b32 s9, s24, 10
	v_and_b32_e32 v4, 0x70, v4
	s_add_i32 s9, s9, 0
	v_lshl_or_b32 v3, v3, 11, v4
	s_mov_b32 m0, s9
	v_add_u32_e32 v5, 0x20000, v3
	global_load_lds_dwordx4 v3, s[18:19]
	s_add_i32 m0, s9, 0x8000
	v_add_u32_e32 v6, 0x40000, v3
	global_load_lds_dwordx4 v3, s[22:23]
	s_add_i32 m0, s9, 0x2000
	v_add_u32_e32 v7, 0x60000, v3
	global_load_lds_dwordx4 v5, s[18:19]
	s_add_i32 m0, s9, 0xa000
	v_and_b32_e32 v1, 15, v0
	global_load_lds_dwordx4 v5, s[22:23]
	s_add_i32 m0, s9, 0x4000
	v_bfe_u32 v8, v0, 4, 2
	global_load_lds_dwordx4 v6, s[18:19]
	s_add_i32 m0, s9, 0xc000
	v_lshrrev_b32_e32 v3, 1, v0
	global_load_lds_dwordx4 v6, s[22:23]
	s_add_i32 m0, s9, 0x6000
	v_bfe_u32 v0, v0, 1, 3
	global_load_lds_dwordx4 v7, s[18:19]
	s_add_i32 m0, s9, 0xe000
	s_lshr_b32 s18, s12, 1
	global_load_lds_dwordx4 v7, s[22:23]
	s_and_b32 s18, s18, 0x1ffff80
	s_and_b32 s12, s12, 0xc0
	v_or_b32_e32 v5, s18, v1
	v_or_b32_e32 v1, s12, v1
	s_lshl_b32 s12, s24, 14
	s_add_u32 s16, s96, s16
	v_lshlrev_b32_e32 v149, 7, v5
	v_bitop3_b32 v0, v8, v0, 4 bitop3:0x36
	v_lshlrev_b32_e32 v5, 11, v2
	s_addc_u32 s17, s97, s17
	s_add_i32 s18, s12, 0x20000
	v_lshlrev_b32_e32 v147, 7, v1
	v_bitop3_b32 v1, v8, v3, 7 bitop3:0x78
	v_lshlrev_b32_e32 v146, 4, v0
	v_or3_b32 v80, s12, v5, v4
	v_or3_b32 v0, s18, v5, v4
	s_add_i32 s18, s12, 0x40000
	s_add_i32 s12, s12, 0x60000
	v_lshlrev_b32_e32 v148, 4, v1
	v_mov_b32_e32 v1, v81
	v_or3_b32 v2, s18, v5, v4
	v_mov_b32_e32 v3, v81
	v_or3_b32 v4, s12, v5, v4
	v_mov_b32_e32 v5, v81
	v_lshl_add_u64 v[130:131], s[16:17], 0, v[80:81]
	v_lshl_add_u64 v[132:133], s[16:17], 0, v[0:1]
	v_lshl_add_u64 v[134:135], s[16:17], 0, v[2:3]
	v_lshl_add_u64 v[136:137], s[16:17], 0, v[4:5]
	s_add_u32 s16, s64, s20
	s_addc_u32 s17, s65, s21
	v_lshl_add_u64 v[140:141], s[16:17], 0, v[0:1]
	v_mov_b32_e32 v0, 0
	v_lshl_add_u64 v[138:139], s[16:17], 0, v[80:81]
	v_lshl_add_u64 v[142:143], s[16:17], 0, v[2:3]
	v_lshl_add_u64 v[144:145], s[16:17], 0, v[4:5]
	s_mov_b32 s12, 0
	s_mov_b64 s[38:39], 0
	v_mov_b32_e32 v1, v0
	v_mov_b32_e32 v2, v0
	v_mov_b32_e32 v3, v0
	v_mov_b32_e32 v4, v0
	v_mov_b32_e32 v5, v0
	v_mov_b32_e32 v6, v0
	v_mov_b32_e32 v7, v0
	v_mov_b32_e32 v8, v0
	v_mov_b32_e32 v9, v0
	v_mov_b32_e32 v10, v0
	v_mov_b32_e32 v11, v0
	v_mov_b32_e32 v12, v0
	v_mov_b32_e32 v13, v0
	v_mov_b32_e32 v14, v0
	v_mov_b32_e32 v15, v0
	v_mov_b32_e32 v16, v0
	v_mov_b32_e32 v17, v0
	v_mov_b32_e32 v18, v0
	v_mov_b32_e32 v19, v0
	v_mov_b32_e32 v20, v0
	v_mov_b32_e32 v21, v0
	v_mov_b32_e32 v22, v0
	v_mov_b32_e32 v23, v0
	v_mov_b32_e32 v24, v0
	v_mov_b32_e32 v25, v0
	v_mov_b32_e32 v26, v0
	v_mov_b32_e32 v27, v0
	v_mov_b32_e32 v28, v0
	v_mov_b32_e32 v29, v0
	v_mov_b32_e32 v30, v0
	v_mov_b32_e32 v31, v0
	v_mov_b32_e32 v32, v0
	v_mov_b32_e32 v33, v0
	v_mov_b32_e32 v34, v0
	v_mov_b32_e32 v35, v0
	v_mov_b32_e32 v36, v0
	v_mov_b32_e32 v37, v0
	v_mov_b32_e32 v38, v0
	v_mov_b32_e32 v39, v0
	v_mov_b32_e32 v40, v0
	v_mov_b32_e32 v41, v0
	v_mov_b32_e32 v42, v0
	v_mov_b32_e32 v43, v0
	v_mov_b32_e32 v44, v0
	v_mov_b32_e32 v45, v0
	v_mov_b32_e32 v46, v0
	v_mov_b32_e32 v47, v0
	v_mov_b32_e32 v48, v0
	v_mov_b32_e32 v49, v0
	v_mov_b32_e32 v50, v0
	v_mov_b32_e32 v51, v0
	v_mov_b32_e32 v52, v0
	v_mov_b32_e32 v53, v0
	v_mov_b32_e32 v54, v0
	v_mov_b32_e32 v55, v0
	v_mov_b32_e32 v56, v0
	v_mov_b32_e32 v57, v0
	v_mov_b32_e32 v58, v0
	v_mov_b32_e32 v59, v0
	v_mov_b32_e32 v60, v0
	v_mov_b32_e32 v61, v0
	v_mov_b32_e32 v62, v0
	v_mov_b32_e32 v63, v0
	v_mov_b32_e32 v64, v0
	v_mov_b32_e32 v65, v0
	v_mov_b32_e32 v66, v0
	v_mov_b32_e32 v67, v0
	v_mov_b32_e32 v68, v0
	v_mov_b32_e32 v69, v0
	v_mov_b32_e32 v70, v0
	v_mov_b32_e32 v71, v0
	v_mov_b32_e32 v72, v0
	v_mov_b32_e32 v73, v0
	v_mov_b32_e32 v74, v0
	v_mov_b32_e32 v75, v0
	v_mov_b32_e32 v76, v0
	v_mov_b32_e32 v77, v0
	v_mov_b32_e32 v78, v0
	v_mov_b32_e32 v79, v0
	v_mov_b32_e32 v82, v0
	v_mov_b32_e32 v83, v0
	v_mov_b32_e32 v84, v0
	v_mov_b32_e32 v85, v0
	v_mov_b32_e32 v86, v0
	v_mov_b32_e32 v87, v0
	v_mov_b32_e32 v88, v0
	v_mov_b32_e32 v89, v0
	v_mov_b32_e32 v90, v0
	v_mov_b32_e32 v91, v0
	v_mov_b32_e32 v92, v0
	v_mov_b32_e32 v93, v0
	v_mov_b32_e32 v94, v0
	v_mov_b32_e32 v95, v0
	v_mov_b32_e32 v96, v0
	v_mov_b32_e32 v97, v0
	v_mov_b32_e32 v98, v0
	v_mov_b32_e32 v99, v0
	v_mov_b32_e32 v100, v0
	v_mov_b32_e32 v101, v0
	v_mov_b32_e32 v102, v0
	v_mov_b32_e32 v103, v0
	v_mov_b32_e32 v104, v0
	v_mov_b32_e32 v105, v0
	v_mov_b32_e32 v106, v0
	v_mov_b32_e32 v107, v0
	v_mov_b32_e32 v108, v0
	v_mov_b32_e32 v109, v0
	v_mov_b32_e32 v110, v0
	v_mov_b32_e32 v111, v0
	v_mov_b32_e32 v112, v0
	v_mov_b32_e32 v113, v0
	v_mov_b32_e32 v114, v0
	v_mov_b32_e32 v115, v0
	v_mov_b32_e32 v116, v0
	v_mov_b32_e32 v117, v0
	v_mov_b32_e32 v118, v0
	v_mov_b32_e32 v119, v0
	v_mov_b32_e32 v120, v0
	v_mov_b32_e32 v121, v0
	v_mov_b32_e32 v122, v0
	v_mov_b32_e32 v123, v0
	v_mov_b32_e32 v124, v0
	v_mov_b32_e32 v125, v0
	v_mov_b32_e32 v126, v0
	v_mov_b32_e32 v127, v0
	v_mov_b32_e32 v128, v0
	v_mov_b32_e32 v129, v0
	s_waitcnt vmcnt(0)
	s_waitcnt lgkmcnt(0)
	s_barrier

; #define LDSAS __attribute__((address_space(3)))
; #define G_ISSUE(kt, st) do { G_ISSUE1(kt, st, 0); G_ISSUE1(kt, st, 1); G_ISSUE1(kt, st, 2); G_ISSUE1(kt, st, 3); } while (0)
; template <bool LOWREG = false>
; __device__ __forceinline__ void gemm_core(const bf16_t* __restrict__ A, int lda, const bf16_t* __restrict__ Bt, int ldb, int K, f32x4 (&acc)[8][4], unsigned char* smem, int tid) {
;     asm volatile("" : "+v"(tid));
;     const int lane = tid & 63, w = __builtin_amdgcn_readfirstlane(tid >> 6), wm = w >> 2, wn = w & 3, idx = lane & 15, kq = lane >> 4;
;     unsigned offA[4], offB[4];
; #pragma unroll
;     for (int j = 0; j < 4; ++j) { const int row = (j * 8 + w) * 8 + (lane >> 3), c = (lane & 7) ^ ((row >> 1) & 7);
;         offA[j] = (unsigned)(row * lda + c * 8) * 2u; offB[j] = (unsigned)(row * ldb + c * 8) * 2u; }
; #pragma unroll
;     for (int mi = 0; mi < 8; ++mi)
; #pragma unroll
;         for (int ni = 0; ni < 4; ++ni) acc[mi][ni] = (f32x4){0.f, 0.f, 0.f, 0.f};
;     LDSAS unsigned char* lds = (LDSAS unsigned char*)smem;
;     ...
;     const int nk = K >> 6;
;     G_ISSUE(0, 0);
;     asm volatile("s_waitcnt vmcnt(0)" ::: "memory");
;     __syncthreads();
;     const int swz = (idx >> 1) & 7;
;     const int aoff = (wm * 128 + idx) * 128, boff = G_AB + (wn * 64 + idx) * 128;
.LBB0_1100:
	s_mul_hi_i32 s19, s17, s67
	s_mul_i32 s18, s17, s67
	s_lshl_b64 s[18:19], s[18:19], 1
	s_add_u32 s18, s40, s18
	s_mul_i32 s9, s17, s88
	s_addc_u32 s19, s41, s19
	s_lshl_b32 s9, s9, 1
	v_mov_b32_e32 v0, v210
	s_add_u32 s20, s38, s9
	s_addc_u32 s21, s39, 0
	v_readfirstlane_b32 s16, v0
	s_ashr_i32 s9, s16, 6
	v_bfe_u32 v2, v0, 3, 3
	v_lshl_or_b32 v8, s9, 3, v2
	v_lshrrev_b32_e32 v2, 1, v8
	v_xor_b32_e32 v3, v2, v0
	v_lshlrev_b32_e32 v3, 3, v3
	v_mul_lo_u32 v4, v8, s17
	v_and_b32_e32 v3, 56, v3
	s_lshl_b32 s9, s9, 10
	v_or_b32_e32 v5, v3, v4
	s_lshl_b32 s22, s17, 6
	s_add_i32 s9, s9, 0
	v_lshlrev_b32_e32 v5, 1, v5
	v_add_u32_e32 v4, s22, v4
	s_mov_b32 m0, s9
	v_or_b32_e32 v6, v3, v4
	global_load_lds_dwordx4 v5, s[18:19]
	s_add_i32 m0, s9, 0x8000
	v_lshlrev_b32_e32 v6, 1, v6
	v_add_u32_e32 v4, s22, v4
	global_load_lds_dwordx4 v5, s[20:21]
	s_add_i32 m0, s9, 0x2000
	v_or_b32_e32 v7, v3, v4
	global_load_lds_dwordx4 v6, s[18:19]
	s_add_i32 m0, s9, 0xa000
	v_lshlrev_b32_e32 v7, 1, v7
	v_add_u32_e32 v4, s22, v4
	global_load_lds_dwordx4 v6, s[20:21]
	s_add_i32 m0, s9, 0x4000
	v_or_b32_e32 v3, v3, v4
	global_load_lds_dwordx4 v7, s[18:19]
	s_add_i32 m0, s9, 0xc000
	v_lshlrev_b32_e32 v3, 1, v3
	global_load_lds_dwordx4 v7, s[20:21]
	s_add_i32 m0, s9, 0x6000
	v_and_b32_e32 v1, 15, v0
	global_load_lds_dwordx4 v3, s[18:19]
	s_add_i32 m0, s9, 0xe000
	s_lshr_b32 s18, s16, 1
	global_load_lds_dwordx4 v3, s[20:21]
	s_and_b32 s18, s18, 0x1ffff80
	s_and_b32 s16, s16, 0xc0
	v_bfe_u32 v4, v0, 4, 2
	v_lshrrev_b32_e32 v3, 1, v0
	v_or_b32_e32 v6, s18, v1
	v_or_b32_e32 v1, s16, v1
	s_lshr_b32 s22, s17, 6
	v_bfe_u32 v5, v0, 1, 3
	v_lshlrev_b32_e32 v197, 7, v1
	v_bitop3_b32 v1, v4, v3, 7 bitop3:0x78
	v_bitop3_b32 v0, v2, 7, v0 bitop3:0x48
	v_lshlrev_b32_e32 v179, 4, v1
	v_bitop3_b32 v1, v4, v5, 4 bitop3:0x36
	s_add_i32 s16, s22, -1
	s_mul_i32 s18, s59, s17
	s_mul_hi_u32 s19, s58, s17
	s_lshl_b32 s22, s17, 1
	v_lshlrev_b32_e32 v0, 4, v0
	s_add_i32 s20, s19, s18
	s_mul_i32 s21, s58, s17
	v_mad_u64_u32 v[2:3], s[18:19], s22, v8, v[0:1]
	v_lshlrev_b32_e32 v80, 4, v1
	s_add_u32 s18, s40, s21
	v_add_u32_e32 v1, 64, v8
	s_addc_u32 s19, s41, s20
	v_mad_u64_u32 v[4:5], s[20:21], s22, v1, v[0:1]
	v_add_u32_e32 v1, 0x80, v8
	v_lshlrev_b32_e32 v196, 7, v6
	s_add_u32 s18, s18, 0x80
	v_mad_u64_u32 v[6:7], s[20:21], s22, v1, v[0:1]
	v_add_u32_e32 v1, 0xc0, v8
	s_mul_i32 s17, s89, s17
	s_addc_u32 s19, s19, 0
	v_mad_u64_u32 v[0:1], s[20:21], s22, v1, v[0:1]
	s_lshl_b32 s17, s17, 1
	v_mov_b32_e32 v3, v81
	v_mov_b32_e32 v5, v81
	v_mov_b32_e32 v7, v81
	v_mov_b32_e32 v1, v81
	s_add_u32 s17, s38, s17
	v_lshl_add_u64 v[180:181], s[18:19], 0, v[2:3]
	v_lshl_add_u64 v[182:183], s[18:19], 0, v[4:5]
	v_lshl_add_u64 v[184:185], s[18:19], 0, v[6:7]
	v_lshl_add_u64 v[186:187], s[18:19], 0, v[0:1]
	s_addc_u32 s19, s39, 0
	s_add_u32 s18, s17, 0x80
	s_addc_u32 s19, s19, 0
	v_lshl_add_u64 v[194:195], s[18:19], 0, v[0:1]
	v_mov_b32_e32 v0, 0
	v_lshl_add_u64 v[188:189], s[18:19], 0, v[2:3]
	v_lshl_add_u64 v[190:191], s[18:19], 0, v[4:5]
	v_lshl_add_u64 v[192:193], s[18:19], 0, v[6:7]
	s_mov_b32 s17, 0
	s_mov_b64 s[38:39], 0
	s_mov_b32 s18, 0
	v_mov_b32_e32 v1, v0
	v_mov_b32_e32 v2, v0
	v_mov_b32_e32 v3, v0
	v_mov_b32_e32 v4, v0
	v_mov_b32_e32 v5, v0
	v_mov_b32_e32 v6, v0
	v_mov_b32_e32 v7, v0
	v_mov_b32_e32 v8, v0
	v_mov_b32_e32 v9, v0
	v_mov_b32_e32 v10, v0
	v_mov_b32_e32 v11, v0
	v_mov_b32_e32 v12, v0
	v_mov_b32_e32 v13, v0
	v_mov_b32_e32 v14, v0
	v_mov_b32_e32 v15, v0
	v_mov_b32_e32 v16, v0
	v_mov_b32_e32 v17, v0
	v_mov_b32_e32 v18, v0
	v_mov_b32_e32 v19, v0
	v_mov_b32_e32 v20, v0
	v_mov_b32_e32 v21, v0
	v_mov_b32_e32 v22, v0
	v_mov_b32_e32 v23, v0
	v_mov_b32_e32 v24, v0
	v_mov_b32_e32 v25, v0
	v_mov_b32_e32 v26, v0
	v_mov_b32_e32 v27, v0
	v_mov_b32_e32 v28, v0
	v_mov_b32_e32 v29, v0
	v_mov_b32_e32 v30, v0
	v_mov_b32_e32 v31, v0
	v_mov_b32_e32 v32, v0
	v_mov_b32_e32 v33, v0
	v_mov_b32_e32 v34, v0
	v_mov_b32_e32 v35, v0
	v_mov_b32_e32 v36, v0
	v_mov_b32_e32 v37, v0
	v_mov_b32_e32 v38, v0
	v_mov_b32_e32 v39, v0
	v_mov_b32_e32 v40, v0
	v_mov_b32_e32 v41, v0
	v_mov_b32_e32 v42, v0
	v_mov_b32_e32 v43, v0
	v_mov_b32_e32 v44, v0
	v_mov_b32_e32 v45, v0
	v_mov_b32_e32 v46, v0
	v_mov_b32_e32 v47, v0
	v_mov_b32_e32 v48, v0
	v_mov_b32_e32 v49, v0
	v_mov_b32_e32 v50, v0
	v_mov_b32_e32 v51, v0
	v_mov_b32_e32 v52, v0
	v_mov_b32_e32 v53, v0
	v_mov_b32_e32 v54, v0
	v_mov_b32_e32 v55, v0
	v_mov_b32_e32 v56, v0
	v_mov_b32_e32 v57, v0
	v_mov_b32_e32 v58, v0
	v_mov_b32_e32 v59, v0
	v_mov_b32_e32 v60, v0
	v_mov_b32_e32 v61, v0
	v_mov_b32_e32 v62, v0
	v_mov_b32_e32 v63, v0
	v_mov_b32_e32 v64, v0
	v_mov_b32_e32 v65, v0
	v_mov_b32_e32 v66, v0
	v_mov_b32_e32 v67, v0
	v_mov_b32_e32 v68, v0
	v_mov_b32_e32 v69, v0
	v_mov_b32_e32 v70, v0
	v_mov_b32_e32 v71, v0
	v_mov_b32_e32 v72, v0
	v_mov_b32_e32 v73, v0
	v_mov_b32_e32 v74, v0
	v_mov_b32_e32 v75, v0
	v_mov_b32_e32 v76, v0
	v_mov_b32_e32 v77, v0
	v_mov_b32_e32 v78, v0
	v_mov_b32_e32 v79, v0
	v_mov_b32_e32 v82, v0
	v_mov_b32_e32 v83, v0
	v_mov_b32_e32 v84, v0
	v_mov_b32_e32 v85, v0
	v_mov_b32_e32 v86, v0
	v_mov_b32_e32 v87, v0
	v_mov_b32_e32 v88, v0
	v_mov_b32_e32 v89, v0
	v_mov_b32_e32 v90, v0
	v_mov_b32_e32 v91, v0
	v_mov_b32_e32 v92, v0
	v_mov_b32_e32 v93, v0
	v_mov_b32_e32 v94, v0
	v_mov_b32_e32 v95, v0
	v_mov_b32_e32 v96, v0
	v_mov_b32_e32 v97, v0
	v_mov_b32_e32 v98, v0
	v_mov_b32_e32 v99, v0
	v_mov_b32_e32 v100, v0
	v_mov_b32_e32 v101, v0
	v_mov_b32_e32 v102, v0
	v_mov_b32_e32 v103, v0
	v_mov_b32_e32 v104, v0
	v_mov_b32_e32 v105, v0
	v_mov_b32_e32 v106, v0
	v_mov_b32_e32 v107, v0
	v_mov_b32_e32 v108, v0
	v_mov_b32_e32 v109, v0
	v_mov_b32_e32 v110, v0
	v_mov_b32_e32 v111, v0
	v_mov_b32_e32 v112, v0
	v_mov_b32_e32 v113, v0
	v_mov_b32_e32 v114, v0
	v_mov_b32_e32 v115, v0
	v_mov_b32_e32 v116, v0
	v_mov_b32_e32 v117, v0
	v_mov_b32_e32 v118, v0
	v_mov_b32_e32 v119, v0
	v_mov_b32_e32 v120, v0
	v_mov_b32_e32 v121, v0
	v_mov_b32_e32 v122, v0
	v_mov_b32_e32 v123, v0
	v_mov_b32_e32 v124, v0
	v_mov_b32_e32 v125, v0
	v_mov_b32_e32 v126, v0
	v_mov_b32_e32 v127, v0
	v_mov_b32_e32 v128, v0
	v_mov_b32_e32 v129, v0
	s_waitcnt vmcnt(0)
	s_waitcnt lgkmcnt(0)
	s_barrier

; #define LDSAS __attribute__((address_space(3)))
; #define G_ISSUE(kt, st) do { G_ISSUE1(kt, st, 0); G_ISSUE1(kt, st, 1); G_ISSUE1(kt, st, 2); G_ISSUE1(kt, st, 3); } while (0)
; template <bool LOWREG = false>
; __device__ __forceinline__ void gemm_core(const bf16_t* __restrict__ A, int lda, const bf16_t* __restrict__ Bt, int ldb, int K, f32x4 (&acc)[8][4], unsigned char* smem, int tid) {
;     asm volatile("" : "+v"(tid));
;     const int lane = tid & 63, w = __builtin_amdgcn_readfirstlane(tid >> 6), wm = w >> 2, wn = w & 3, idx = lane & 15, kq = lane >> 4;
;     unsigned offA[4], offB[4];
; #pragma unroll
;     for (int j = 0; j < 4; ++j) { const int row = (j * 8 + w) * 8 + (lane >> 3), c = (lane & 7) ^ ((row >> 1) & 7);
;         offA[j] = (unsigned)(row * lda + c * 8) * 2u; offB[j] = (unsigned)(row * ldb + c * 8) * 2u; }
; #pragma unroll
;     for (int mi = 0; mi < 8; ++mi)
; #pragma unroll
;         for (int ni = 0; ni < 4; ++ni) acc[mi][ni] = (f32x4){0.f, 0.f, 0.f, 0.f};
;     LDSAS unsigned char* lds = (LDSAS unsigned char*)smem;
;     ...
;     const int nk = K >> 6;
;     G_ISSUE(0, 0);
;     asm volatile("s_waitcnt vmcnt(0)" ::: "memory");
;     __syncthreads();
;     const int swz = (idx >> 1) & 7;
;     const int aoff = (wm * 128 + idx) * 128, boff = G_AB + (wn * 64 + idx) * 128;
; __device__ void out_phase(const Params& p, int l, int hb, const float* xsrc, unsigned char* smem) {
;     ...
;     for (int t = blockIdx.x; t < 64 * 4; t += gridDim.x) {
;         const int xq = t >> 3, mt = (xq >> 2) * 8 + (t & 7), nt = xq & 3, m0 = mt * 256, n0 = nt * 256;
;         f32x4 acc[8][4];
;         int tid = threadIdx.x;
;         gemm_core(MR + (size_t)m0 * 1024, 1024, Wt + (size_t)n0 * 1024, 1024, 1024, acc, smem, tid);
.LBB0_1285:
	s_and_b32 s24, s22, 7
	s_lshl_b32 s30, s24, 8
	s_lshl_b32 s24, s21, 11
	s_ashr_i32 s44, s23, 2
	s_and_b32 s31, s24, 0x180000
	s_and_b32 s24, s44, 0xfffff8
	s_and_b32 s25, s23, 7
	s_or_b32 s24, s24, s25
	s_lshl_b32 s42, s24, 8
	s_lshl_b32 s24, s23, 5
	s_ashr_i32 s43, s42, 31
	s_and_b32 s24, s24, 0x300
	s_lshl_b64 s[26:27], s[42:43], 11
	s_add_u32 s26, s9, s26
	s_addc_u32 s27, s11, s27
	s_lshl_b32 s25, s24, 11
	v_mov_b32_e32 v0, v210
	s_add_u32 s28, s12, s25
	s_addc_u32 s29, s16, 0
	v_readfirstlane_b32 s43, v0
	s_ashr_i32 s45, s43, 6
	v_bfe_u32 v2, v0, 3, 3
	v_lshl_or_b32 v3, s45, 3, v2
	v_lshrrev_b32_e32 v4, 1, v3
	v_xor_b32_e32 v4, v4, v0
	v_lshlrev_b32_e32 v4, 4, v4
	s_lshl_b32 s25, s45, 10
	v_and_b32_e32 v4, 0x70, v4
	s_add_i32 s25, s25, 0
	v_lshl_or_b32 v3, v3, 11, v4
	s_mov_b32 m0, s25
	v_add_u32_e32 v5, 0x20000, v3
	global_load_lds_dwordx4 v3, s[26:27]
	s_add_i32 m0, s25, 0x8000
	v_add_u32_e32 v6, 0x40000, v3
	global_load_lds_dwordx4 v3, s[28:29]
	s_add_i32 m0, s25, 0x2000
	v_add_u32_e32 v7, 0x60000, v3
	global_load_lds_dwordx4 v5, s[26:27]
	s_add_i32 m0, s25, 0xa000
	v_and_b32_e32 v1, 15, v0
	global_load_lds_dwordx4 v5, s[28:29]
	s_add_i32 m0, s25, 0x4000
	v_bfe_u32 v8, v0, 4, 2
	global_load_lds_dwordx4 v6, s[26:27]
	s_add_i32 m0, s25, 0xc000
	v_lshrrev_b32_e32 v3, 1, v0
	global_load_lds_dwordx4 v6, s[28:29]
	s_add_i32 m0, s25, 0x6000
	v_bfe_u32 v0, v0, 1, 3
	global_load_lds_dwordx4 v7, s[26:27]
	s_add_i32 m0, s25, 0xe000
	s_lshr_b32 s26, s43, 1
	global_load_lds_dwordx4 v7, s[28:29]
	s_and_b32 s26, s26, 0x1ffff80
	v_or_b32_e32 v5, s26, v1
	s_and_b32 s26, s43, 0xc0
	v_or_b32_e32 v1, s26, v1
	s_lshl_b32 s26, s44, 8
	s_and_b32 s26, s26, 0xfffff800
	s_or_b32 s26, s26, s30
	s_ashr_i32 s27, s26, 31
	s_lshl_b64 s[26:27], s[26:27], 11
	s_lshl_b32 s28, s45, 14
	s_add_u32 s26, s17, s26
	v_lshlrev_b32_e32 v149, 7, v5
	v_bitop3_b32 v0, v8, v0, 4 bitop3:0x36
	v_lshlrev_b32_e32 v5, 11, v2
	s_addc_u32 s27, s18, s27
	s_add_i32 s29, s28, 0x20000
	v_lshlrev_b32_e32 v147, 7, v1
	v_bitop3_b32 v1, v8, v3, 7 bitop3:0x78
	v_lshlrev_b32_e32 v146, 4, v0
	v_or3_b32 v80, s28, v5, v4
	v_or3_b32 v0, s29, v5, v4
	s_add_i32 s29, s28, 0x40000
	s_add_i32 s28, s28, 0x60000
	v_lshlrev_b32_e32 v148, 4, v1
	v_mov_b32_e32 v1, v81
	v_or3_b32 v2, s29, v5, v4
	v_mov_b32_e32 v3, v81
	v_or3_b32 v4, s28, v5, v4
	v_mov_b32_e32 v5, v81
	v_lshl_add_u64 v[130:131], s[26:27], 0, v[80:81]
	v_lshl_add_u64 v[132:133], s[26:27], 0, v[0:1]
	v_lshl_add_u64 v[134:135], s[26:27], 0, v[2:3]
	v_lshl_add_u64 v[136:137], s[26:27], 0, v[4:5]
	s_add_u32 s26, s19, s31
	s_addc_u32 s27, s20, 0
	v_lshl_add_u64 v[140:141], s[26:27], 0, v[0:1]
	v_mov_b32_e32 v0, 0
	v_lshl_add_u64 v[138:139], s[26:27], 0, v[80:81]
	v_lshl_add_u64 v[142:143], s[26:27], 0, v[2:3]
	v_lshl_add_u64 v[144:145], s[26:27], 0, v[4:5]
	s_mov_b32 s26, 0
	s_mov_b64 s[44:45], 0
	v_mov_b32_e32 v1, v0
	v_mov_b32_e32 v2, v0
	v_mov_b32_e32 v3, v0
	v_mov_b32_e32 v4, v0
	v_mov_b32_e32 v5, v0
	v_mov_b32_e32 v6, v0
	v_mov_b32_e32 v7, v0
	v_mov_b32_e32 v8, v0
	v_mov_b32_e32 v9, v0
	v_mov_b32_e32 v10, v0
	v_mov_b32_e32 v11, v0
	v_mov_b32_e32 v12, v0
	v_mov_b32_e32 v13, v0
	v_mov_b32_e32 v14, v0
	v_mov_b32_e32 v15, v0
	v_mov_b32_e32 v16, v0
	v_mov_b32_e32 v17, v0
	v_mov_b32_e32 v18, v0
	v_mov_b32_e32 v19, v0
	v_mov_b32_e32 v20, v0
	v_mov_b32_e32 v21, v0
	v_mov_b32_e32 v22, v0
	v_mov_b32_e32 v23, v0
	v_mov_b32_e32 v24, v0
	v_mov_b32_e32 v25, v0
	v_mov_b32_e32 v26, v0
	v_mov_b32_e32 v27, v0
	v_mov_b32_e32 v28, v0
	v_mov_b32_e32 v29, v0
	v_mov_b32_e32 v30, v0
	v_mov_b32_e32 v31, v0
	v_mov_b32_e32 v32, v0
	v_mov_b32_e32 v33, v0
	v_mov_b32_e32 v34, v0
	v_mov_b32_e32 v35, v0
	v_mov_b32_e32 v36, v0
	v_mov_b32_e32 v37, v0
	v_mov_b32_e32 v38, v0
	v_mov_b32_e32 v39, v0
	v_mov_b32_e32 v40, v0
	v_mov_b32_e32 v41, v0
	v_mov_b32_e32 v42, v0
	v_mov_b32_e32 v43, v0
	v_mov_b32_e32 v44, v0
	v_mov_b32_e32 v45, v0
	v_mov_b32_e32 v46, v0
	v_mov_b32_e32 v47, v0
	v_mov_b32_e32 v48, v0
	v_mov_b32_e32 v49, v0
	v_mov_b32_e32 v50, v0
	v_mov_b32_e32 v51, v0
	v_mov_b32_e32 v52, v0
	v_mov_b32_e32 v53, v0
	v_mov_b32_e32 v54, v0
	v_mov_b32_e32 v55, v0
	v_mov_b32_e32 v56, v0
	v_mov_b32_e32 v57, v0
	v_mov_b32_e32 v58, v0
	v_mov_b32_e32 v59, v0
	v_mov_b32_e32 v60, v0
	v_mov_b32_e32 v61, v0
	v_mov_b32_e32 v62, v0
	v_mov_b32_e32 v63, v0
	v_mov_b32_e32 v64, v0
	v_mov_b32_e32 v65, v0
	v_mov_b32_e32 v66, v0
	v_mov_b32_e32 v67, v0
	v_mov_b32_e32 v68, v0
	v_mov_b32_e32 v69, v0
	v_mov_b32_e32 v70, v0
	v_mov_b32_e32 v71, v0
	v_mov_b32_e32 v72, v0
	v_mov_b32_e32 v73, v0
	v_mov_b32_e32 v74, v0
	v_mov_b32_e32 v75, v0
	v_mov_b32_e32 v76, v0
	v_mov_b32_e32 v77, v0
	v_mov_b32_e32 v78, v0
	v_mov_b32_e32 v79, v0
	v_mov_b32_e32 v82, v0
	v_mov_b32_e32 v83, v0
	v_mov_b32_e32 v84, v0
	v_mov_b32_e32 v85, v0
	v_mov_b32_e32 v86, v0
	v_mov_b32_e32 v87, v0
	v_mov_b32_e32 v88, v0
	v_mov_b32_e32 v89, v0
	v_mov_b32_e32 v90, v0
	v_mov_b32_e32 v91, v0
	v_mov_b32_e32 v92, v0
	v_mov_b32_e32 v93, v0
	v_mov_b32_e32 v94, v0
	v_mov_b32_e32 v95, v0
	v_mov_b32_e32 v96, v0
	v_mov_b32_e32 v97, v0
	v_mov_b32_e32 v98, v0
	v_mov_b32_e32 v99, v0
	v_mov_b32_e32 v100, v0
	v_mov_b32_e32 v101, v0
	v_mov_b32_e32 v102, v0
	v_mov_b32_e32 v103, v0
	v_mov_b32_e32 v104, v0
	v_mov_b32_e32 v105, v0
	v_mov_b32_e32 v106, v0
	v_mov_b32_e32 v107, v0
	v_mov_b32_e32 v108, v0
	v_mov_b32_e32 v109, v0
	v_mov_b32_e32 v110, v0
	v_mov_b32_e32 v111, v0
	v_mov_b32_e32 v112, v0
	v_mov_b32_e32 v113, v0
	v_mov_b32_e32 v114, v0
	v_mov_b32_e32 v115, v0
	v_mov_b32_e32 v116, v0
	v_mov_b32_e32 v117, v0
	v_mov_b32_e32 v118, v0
	v_mov_b32_e32 v119, v0
	v_mov_b32_e32 v120, v0
	v_mov_b32_e32 v121, v0
	v_mov_b32_e32 v122, v0
	v_mov_b32_e32 v123, v0
	v_mov_b32_e32 v124, v0
	v_mov_b32_e32 v125, v0
	v_mov_b32_e32 v126, v0
	v_mov_b32_e32 v127, v0
	v_mov_b32_e32 v128, v0
	v_mov_b32_e32 v129, v0
	s_waitcnt vmcnt(0)
	s_waitcnt lgkmcnt(0)
	s_barrier
